# P2a: nine row pairs of stage 1 loaded up front ahead of the weight loads instead of one round trip per row
# speedup vs baseline: 1.0234x; 1.0014x over previous
.LBB0_226:
	v_mov_b32_e32 v20, v161
	v_ashrrev_i32_e32 v144, 6, v20
	v_lshlrev_b32_e32 v144, 3, v144
	v_add_u32_e32 v144, s28, v144
	v_subrev_u32_e32 v145, 51, v144
	v_and_b32_e32 v146, 0x7f8, v145
	v_cmp_ne_u32_e64 s[98:99], 0, v146
	v_and_b32_e32 v147, 63, v20
	v_lshlrev_b32_e32 v147, 1, v147
	v_mul_u32_u24_e32 v148, 0x2200, v145
	v_add3_u32 v148, v148, v147, s63
	v_cndmask_b32_e64 v149, 0, v240, s[98:99]
	v_sub_u32_e32 v149, v148, v149
	global_load_ushort v150, v149, s[16:17] offset:32
	global_load_ushort v151, v149, s[16:17] offset:160
	global_load_ushort v152, v148, s[16:17] offset:32
	global_load_ushort v153, v148, s[16:17] offset:160
	v_add_u32_e32 v148, 0x2200, v148
	global_load_ushort v154, v148, s[16:17] offset:32
	global_load_ushort v155, v148, s[16:17] offset:160
	v_add_u32_e32 v148, 0x2200, v148
	global_load_ushort v168, v148, s[16:17] offset:32
	global_load_ushort v169, v148, s[16:17] offset:160
	v_add_u32_e32 v148, 0x2200, v148
	global_load_ushort v170, v148, s[16:17] offset:32
	global_load_ushort v171, v148, s[16:17] offset:160
	v_add_u32_e32 v148, 0x2200, v148
	global_load_ushort v172, v148, s[16:17] offset:32
	global_load_ushort v173, v148, s[16:17] offset:160
	v_add_u32_e32 v148, 0x2200, v148
	global_load_ushort v176, v148, s[16:17] offset:32
	global_load_ushort v177, v148, s[16:17] offset:160
	v_add_u32_e32 v148, 0x2200, v148
	global_load_ushort v178, v148, s[16:17] offset:32
	global_load_ushort v179, v148, s[16:17] offset:160
	v_add_u32_e32 v148, 0x2200, v148
	global_load_ushort v180, v148, s[16:17] offset:32
	global_load_ushort v181, v148, s[16:17] offset:160
	v_mov_b32_e32 v9, v3
	v_ashrrev_i32_e32 v38, 6, v20
	v_and_b32_e32 v183, 15, v20
	v_readfirstlane_b32 s2, v38
	v_bfe_u32 v182, v20, 4, 2
	v_lshlrev_b32_e32 v36, 11, v182
	v_lshl_or_b32 v0, s2, 5, v183
	v_ashrrev_i32_e32 v1, 31, v0
	v_or_b32_e32 v8, 0x400, v36
	v_lshl_add_u64 v[8:9], v[0:1], 0, v[8:9]
	v_lshlrev_b64 v[10:11], 2, v[8:9]
	v_lshl_add_u64 v[50:51], s[12:13], 0, v[10:11]
	v_lshl_add_u64 v[52:53], s[22:23], 0, v[10:11]
	v_or_b32_e32 v10, 0x500, v36
	v_mov_b32_e32 v11, v3
	v_lshl_add_u64 v[10:11], v[0:1], 0, v[10:11]
	v_lshlrev_b64 v[10:11], 2, v[10:11]
	v_lshl_add_u64 v[54:55], s[12:13], 0, v[10:11]
	v_lshl_add_u64 v[56:57], s[22:23], 0, v[10:11]
	v_or_b32_e32 v10, 0x600, v36
	v_mov_b32_e32 v11, v3
	v_lshl_add_u64 v[10:11], v[0:1], 0, v[10:11]
	v_lshlrev_b64 v[12:13], 2, v[10:11]
	v_lshl_add_u64 v[58:59], s[12:13], 0, v[12:13]
	v_lshl_add_u64 v[60:61], s[22:23], 0, v[12:13]
	v_or_b32_e32 v12, 0x700, v36
	v_mov_b32_e32 v13, v3
	v_lshl_add_u64 v[12:13], v[0:1], 0, v[12:13]
	v_or_b32_e32 v2, 0x2000, v36
	v_lshlrev_b64 v[12:13], 2, v[12:13]
	v_lshl_add_u64 v[62:63], s[12:13], 0, v[12:13]
	v_lshl_add_u64 v[64:65], s[22:23], 0, v[12:13]
	v_lshl_add_u64 v[12:13], v[0:1], 0, v[2:3]
	v_lshlrev_b64 v[14:15], 2, v[12:13]
	v_or_b32_e32 v2, 0x2100, v36
	v_lshl_add_u64 v[66:67], s[12:13], 0, v[14:15]
	v_lshl_add_u64 v[68:69], s[22:23], 0, v[14:15]
	v_lshl_add_u64 v[14:15], v[0:1], 0, v[2:3]
	v_lshlrev_b64 v[14:15], 2, v[14:15]
	v_or_b32_e32 v2, 0x2200, v36
	v_lshl_add_u64 v[70:71], s[12:13], 0, v[14:15]
	v_lshl_add_u64 v[72:73], s[22:23], 0, v[14:15]
	v_lshl_add_u64 v[14:15], v[0:1], 0, v[2:3]
	v_lshlrev_b64 v[16:17], 2, v[14:15]
	v_or_b32_e32 v2, 0x2300, v36
	v_lshl_add_u64 v[74:75], s[12:13], 0, v[16:17]
	v_lshl_add_u64 v[76:77], s[22:23], 0, v[16:17]
	v_lshl_add_u64 v[16:17], v[0:1], 0, v[2:3]
	v_lshlrev_b64 v[16:17], 2, v[16:17]
	v_or_b32_e32 v2, 0x2400, v36
	v_lshl_add_u64 v[78:79], s[12:13], 0, v[16:17]
	v_lshl_add_u64 v[80:81], s[22:23], 0, v[16:17]
	v_lshl_add_u64 v[16:17], v[0:1], 0, v[2:3]
	v_lshlrev_b64 v[18:19], 2, v[16:17]
	v_or_b32_e32 v2, 0x2500, v36
	v_lshl_add_u64 v[82:83], s[12:13], 0, v[18:19]
	v_lshl_add_u64 v[84:85], s[22:23], 0, v[18:19]
	v_lshl_add_u64 v[18:19], v[0:1], 0, v[2:3]
	v_lshlrev_b64 v[18:19], 2, v[18:19]
	v_or_b32_e32 v2, 0x2600, v36
	v_mov_b32_e32 v37, v3
	v_lshl_add_u64 v[86:87], s[12:13], 0, v[18:19]
	v_lshl_add_u64 v[88:89], s[22:23], 0, v[18:19]
	v_lshl_add_u64 v[18:19], v[0:1], 0, v[2:3]
	v_or_b32_e32 v2, 0x2700, v36
	v_lshl_add_u64 v[4:5], v[0:1], 0, v[36:37]
	v_or_b32_e32 v44, 0x100, v36
	v_or_b32_e32 v46, 0x200, v36
	v_or_b32_e32 v48, 0x300, v36
	v_lshl_add_u64 v[36:37], v[0:1], 0, v[2:3]
	v_lshlrev_b64 v[6:7], 2, v[4:5]
	v_lshlrev_b64 v[90:91], 2, v[18:19]
	v_lshlrev_b64 v[36:37], 2, v[36:37]
	v_lshl_add_u64 v[40:41], s[12:13], 0, v[6:7]
	v_lshl_add_u64 v[42:43], s[22:23], 0, v[6:7]
	v_mov_b32_e32 v45, v3
	v_lshl_add_u64 v[92:93], s[12:13], 0, v[90:91]
	v_lshl_add_u64 v[90:91], s[22:23], 0, v[90:91]
	v_lshl_add_u64 v[94:95], s[12:13], 0, v[36:37]
	v_lshl_add_u64 v[96:97], s[22:23], 0, v[36:37]
	global_load_dword v4, v[40:41], off
	global_load_dword v21, v[42:43], off
	global_load_dword v5, v[40:41], off offset:1024
	global_load_dword v22, v[42:43], off offset:1024
	global_load_dword v6, v[40:41], off offset:2048
	global_load_dword v23, v[42:43], off offset:2048
	global_load_dword v7, v[40:41], off offset:3072
	global_load_dword v24, v[42:43], off offset:3072
	global_load_dword v8, v[50:51], off
	global_load_dword v25, v[52:53], off
	global_load_dword v9, v[54:55], off
	global_load_dword v26, v[56:57], off
	global_load_dword v10, v[58:59], off
	global_load_dword v27, v[60:61], off
	global_load_dword v11, v[62:63], off
	global_load_dword v28, v[64:65], off
	global_load_dword v12, v[66:67], off
	global_load_dword v29, v[68:69], off
	global_load_dword v13, v[70:71], off
	global_load_dword v30, v[72:73], off
	global_load_dword v14, v[74:75], off
	global_load_dword v31, v[76:77], off
	global_load_dword v15, v[78:79], off
	global_load_dword v32, v[80:81], off
	global_load_dword v16, v[82:83], off
	global_load_dword v33, v[84:85], off
	global_load_dword v17, v[86:87], off
	global_load_dword v34, v[88:89], off
	global_load_dword v35, v[90:91], off
	global_load_dword v18, v[92:93], off
	global_load_dword v19, v[94:95], off
	global_load_dword v36, v[96:97], off
	global_load_dword v118, v[40:41], off offset:64
	global_load_dword v217, v[42:43], off offset:64
	v_lshl_add_u64 v[40:41], v[0:1], 0, v[44:45]
	v_lshlrev_b64 v[40:41], 2, v[40:41]
	v_mov_b32_e32 v47, v3
	v_lshl_add_u64 v[42:43], s[12:13], 0, v[40:41]
	v_lshl_add_u64 v[40:41], s[22:23], 0, v[40:41]
	global_load_dword v224, v[40:41], off offset:64
	v_lshl_add_u64 v[40:41], v[0:1], 0, v[46:47]
	v_lshlrev_b64 v[40:41], 2, v[40:41]
	v_mov_b32_e32 v49, v3
	global_load_dword v119, v[42:43], off offset:64
	v_lshl_add_u64 v[42:43], s[12:13], 0, v[40:41]
	v_lshl_add_u64 v[40:41], s[22:23], 0, v[40:41]
	global_load_dword v225, v[40:41], off offset:64
	v_lshl_add_u64 v[40:41], v[0:1], 0, v[48:49]
	v_and_b32_e32 v117, 63, v20
	v_lshlrev_b64 v[40:41], 2, v[40:41]
	global_load_dword v122, v[42:43], off offset:64
	v_lshl_add_u64 v[42:43], s[12:13], 0, v[40:41]
	v_lshl_add_u64 v[40:41], s[22:23], 0, v[40:41]
	v_lshlrev_b32_e32 v2, 2, v117
	global_load_dword v123, v[42:43], off offset:64
	global_load_dword v243, v[40:41], off offset:64
	global_load_dword v134, v[50:51], off offset:64
	global_load_dword v228, v[52:53], off offset:64
	global_load_dword v135, v[54:55], off offset:64
	global_load_dword v242, v[56:57], off offset:64
	global_load_dword v132, v[58:59], off offset:64
	global_load_dword v226, v[60:61], off offset:64
	global_load_dword v133, v[62:63], off offset:64
	global_load_dword v229, v[64:65], off offset:64
	global_load_dword v130, v[66:67], off offset:64
	global_load_dword v222, v[68:69], off offset:64
	global_load_dword v131, v[70:71], off offset:64
	global_load_dword v227, v[72:73], off offset:64
	global_load_dword v128, v[74:75], off offset:64
	global_load_dword v220, v[76:77], off offset:64
	global_load_dword v129, v[78:79], off offset:64
	global_load_dword v223, v[80:81], off offset:64
	global_load_dword v126, v[82:83], off offset:64
	global_load_dword v218, v[84:85], off offset:64
	global_load_dword v127, v[86:87], off offset:64
	global_load_dword v221, v[88:89], off offset:64
	global_load_dword v124, v[92:93], off offset:64
	global_load_dword v216, v[90:91], off offset:64
	global_load_dword v125, v[94:95], off offset:64
	global_load_dword v219, v[96:97], off offset:64
	global_load_dword v39, v2, s[24:25] offset:3072
	global_load_dword v37, v2, s[24:25] offset:3328
	v_and_b32_e32 v20, 48, v20
	s_waitcnt vmcnt(62)
	v_cvt_pk_bf16_f32 v76, v4, v5
	s_waitcnt vmcnt(59)
	v_cvt_pk_bf16_f32 v77, v6, v7
	s_waitcnt vmcnt(55)
	v_cvt_pk_bf16_f32 v78, v8, v9
	v_cvt_pk_bf16_f32 v88, v21, v22
	v_cvt_pk_bf16_f32 v89, v23, v24
	s_waitcnt vmcnt(54)
	v_cvt_pk_bf16_f32 v90, v25, v26
	s_waitcnt vmcnt(51)
	v_cvt_pk_bf16_f32 v79, v10, v11
	s_waitcnt vmcnt(50)
	v_cvt_pk_bf16_f32 v91, v27, v28
	s_waitcnt vmcnt(47)
	v_cvt_pk_bf16_f32 v108, v12, v13
	s_waitcnt vmcnt(46)
	v_cvt_pk_bf16_f32 v100, v29, v30
	s_waitcnt vmcnt(43)
	v_cvt_pk_bf16_f32 v109, v14, v15
	s_waitcnt vmcnt(42)
	v_cvt_pk_bf16_f32 v101, v31, v32
	s_waitcnt vmcnt(39)
	v_cvt_pk_bf16_f32 v110, v16, v17
	s_waitcnt vmcnt(38)
	v_cvt_pk_bf16_f32 v102, v33, v34
	s_waitcnt vmcnt(34)
	v_cvt_pk_bf16_f32 v103, v35, v36
	v_cvt_pk_bf16_f32 v111, v18, v19
	v_lshlrev_b32_e32 v43, 16, v150
	v_cndmask_b32_e64 v56, 0, v43, s[98:99]
	s_waitcnt vmcnt(0)
	v_lshlrev_b32_e32 v40, 16, v151
	v_cndmask_b32_e64 v54, 0, v40, s[98:99]
	s_nop 1
	v_lshlrev_b32_e32 v53, 16, v153
	v_lshlrev_b32_e32 v55, 16, v152
	v_sub_f32_e32 v56, v56, v55
	v_sub_f32_e32 v54, v54, v53
	v_fma_f32 v56, v39, v56, v55
	v_fma_f32 v54, v37, v54, v53
	v_add_f32_e32 v56, v56, v56
	v_cvt_pk_bf16_f32 v54, v54, s0
	v_mul_f32_e32 v56, 0xbfb8aa3b, v56
	v_exp_f32_e32 v56, v56
	v_lshlrev_b32_e32 v51, 16, v154
	v_add_f32_e32 v56, 1.0, v56
	v_lshlrev_b32_e32 v50, 16, v155
	v_sub_f32_e32 v53, v53, v50
	s_nop 0
	v_fma_f32 v53, v37, v53, v50
	v_rcp_f32_e32 v56, v56
	v_cvt_pk_bf16_f32 v53, v53, s0
	v_fma_f32 v56, v56, 2.0, -1.0
	v_cvt_pk_bf16_f32 v57, v56, v56
	v_lshlrev_b32_e32 v49, 16, v169
	v_lshlrev_b32_e32 v52, 16, v168
	v_sub_f32_e32 v50, v50, v49
	v_fma_f32 v50, v37, v50, v49
	v_cvt_pk_bf16_f32 v50, v50, s0
	v_lshlrev_b32_e32 v48, 16, v170
	v_lshlrev_b32_e32 v46, 16, v171
	v_sub_f32_e32 v49, v49, v46
	s_nop 0
	v_fma_f32 v49, v37, v49, v46
	v_cvt_pk_bf16_f32 v49, v49, s0
	v_lshlrev_b32_e32 v45, 16, v173
	s_nop 0
	v_lshlrev_b32_e32 v47, 16, v172
	v_sub_f32_e32 v46, v46, v45
	v_fma_f32 v46, v37, v46, v45
	v_cvt_pk_bf16_f32 v46, v46, s0
	v_lshlrev_b32_e32 v42, 16, v176
	v_lshlrev_b32_e32 v41, 16, v177
	s_nop 0
	s_nop 0
	s_movk_i32 s2, 0x240
	v_mul_lo_u32 v38, v38, s2
	v_or_b32_e32 v38, v38, v117
	v_lshl_add_u32 v38, v38, 1, 0
	ds_write_b16 v38, v54 offset:18432
	v_sub_f32_e32 v54, v55, v51
	v_fma_f32 v54, v39, v54, v51
	v_add_f32_e32 v54, v54, v54
	v_mul_f32_e32 v54, 0xbfb8aa3b, v54
	v_sub_f32_e32 v51, v51, v52
	v_exp_f32_e32 v54, v54
	v_fma_f32 v51, v39, v51, v52
	v_add_f32_e32 v51, v51, v51
	v_mul_f32_e32 v51, 0xbfb8aa3b, v51
	v_exp_f32_e32 v51, v51
	ds_write_b16 v38, v50 offset:18720
	v_sub_f32_e32 v50, v52, v48
	v_add_f32_e32 v54, 1.0, v54
	v_fma_f32 v50, v39, v50, v48
	v_rcp_f32_e32 v54, v54
	v_add_f32_e32 v50, v50, v50
	v_mul_f32_e32 v50, 0xbfb8aa3b, v50
	v_sub_f32_e32 v48, v48, v47
	v_add_f32_e32 v51, 1.0, v51
	v_exp_f32_e32 v50, v50
	v_fma_f32 v48, v39, v48, v47
	v_rcp_f32_e32 v51, v51
	v_add_f32_e32 v48, v48, v48
	v_sub_f32_e32 v45, v45, v41
	v_fma_f32 v54, v54, 2.0, -1.0
	v_mul_f32_e32 v48, 0xbfb8aa3b, v48
	ds_write_b16 v38, v46 offset:19008
	v_sub_f32_e32 v46, v47, v42
	v_fma_f32 v45, v37, v45, v41
	v_cvt_pk_bf16_f32 v55, v54, v54
	v_exp_f32_e32 v48, v48
	v_fma_f32 v46, v39, v46, v42
	v_add_f32_e32 v50, 1.0, v50
	v_add_f32_e32 v46, v46, v46
	v_fma_f32 v51, v51, 2.0, -1.0
	v_rcp_f32_e32 v50, v50
	v_mul_f32_e32 v46, 0xbfb8aa3b, v46
	ds_write_b16 v38, v53 offset:18576
	v_cvt_pk_bf16_f32 v53, v51, v51
	v_exp_f32_e32 v46, v46
	v_add_f32_e32 v48, 1.0, v48
	v_rcp_f32_e32 v48, v48
	v_fma_f32 v50, v50, 2.0, -1.0
	v_add_f32_e32 v46, 1.0, v46
	v_rcp_f32_e32 v46, v46
	v_fma_f32 v48, v48, 2.0, -1.0
	ds_write_b16 v38, v49 offset:18864
	v_cvt_pk_bf16_f32 v49, v48, v48
	v_fma_f32 v46, v46, 2.0, -1.0
	v_cvt_pk_bf16_f32 v47, v46, v46
	v_cvt_pk_bf16_f32 v45, v45, s0
	ds_write_b16 v38, v45 offset:19152
	ds_write_b16 v38, v57
	ds_write_b16 v38, v55 offset:144
	ds_write_b16 v38, v53 offset:288
	ds_write_b16 v38, v49 offset:576
	ds_write_b16 v38, v47 offset:720
	v_lshlrev_b32_e32 v44, 16, v178
	v_sub_f32_e32 v42, v42, v44
	v_fma_f32 v42, v39, v42, v44
	v_lshlrev_b32_e32 v43, 16, v180
	v_lshlrev_b32_e32 v40, 16, v179
	v_lshlrev_b32_e32 v58, 16, v57
	v_sub_f32_e32 v56, v56, v58
	v_sub_f32_e32 v41, v41, v40
	v_cvt_pk_bf16_f32 v56, v56, s0
	v_fma_f32 v41, v37, v41, v40
	ds_write_b16 v38, v56 offset:9216
	v_lshlrev_b32_e32 v56, 16, v55
	v_cvt_pk_bf16_f32 v41, v41, s0
	v_sub_f32_e32 v54, v54, v56
	ds_write_b16 v38, v41 offset:19296
	v_sub_f32_e32 v41, v44, v43
	v_cvt_pk_bf16_f32 v54, v54, s0
	v_fmac_f32_e32 v43, v39, v41
	ds_write_b16 v38, v54 offset:9360
	v_lshlrev_b32_e32 v54, 16, v53
	v_add_f32_e32 v42, v42, v42
	v_add_f32_e32 v39, v43, v43
	v_sub_f32_e32 v51, v51, v54
	v_mul_f32_e32 v42, 0xbfb8aa3b, v42
	v_mul_f32_e32 v39, 0xbfb8aa3b, v39
	v_cvt_pk_bf16_f32 v51, v51, s0
	v_exp_f32_e32 v42, v42
	v_exp_f32_e32 v39, v39
	ds_write_b16 v38, v51 offset:9504
	v_cvt_pk_bf16_f32 v51, v50, v50
	v_lshlrev_b32_e32 v52, 16, v51
	v_sub_f32_e32 v50, v50, v52
	v_cvt_pk_bf16_f32 v50, v50, s0
	v_add_f32_e32 v42, 1.0, v42
	v_add_f32_e32 v39, 1.0, v39
	ds_write_b16 v38, v50 offset:9648
	v_lshlrev_b32_e32 v50, 16, v49
	v_rcp_f32_e32 v42, v42
	v_rcp_f32_e32 v39, v39
	v_sub_f32_e32 v48, v48, v50
	v_cvt_pk_bf16_f32 v48, v48, s0
	ds_write_b16 v38, v48 offset:9792
	v_lshlrev_b32_e32 v48, 16, v47
	v_sub_f32_e32 v46, v46, v48
	v_fma_f32 v42, v42, 2.0, -1.0
	v_fma_f32 v39, v39, 2.0, -1.0
	v_cvt_pk_bf16_f32 v46, v46, s0
	v_cvt_pk_bf16_f32 v45, v42, v42
	ds_write_b16 v38, v46 offset:9936
	v_lshlrev_b32_e32 v46, 16, v45
	v_sub_f32_e32 v42, v42, v46
	v_cvt_pk_bf16_f32 v42, v42, s0
	ds_write_b16 v38, v51 offset:432
	ds_write_b16 v38, v45 offset:864
	ds_write_b16 v38, v42 offset:10080
	v_lshlrev_b32_e32 v2, 16, v181
	v_sub_f32_e32 v40, v40, v2
	v_fmac_f32_e32 v2, v37, v40
	v_cvt_pk_bf16_f32 v37, v39, v39
	v_lshlrev_b32_e32 v40, 16, v37
	ds_write_b16 v38, v37 offset:1008
	v_sub_f32_e32 v37, v39, v40
	v_cvt_pk_bf16_f32 v37, v37, s0
	v_cvt_pk_bf16_f32 v2, v2, s0
	ds_write_b16 v38, v37 offset:10224
	ds_write_b16 v38, v2 offset:19440
	v_lshlrev_b32_e32 v38, 16, v76
	v_and_b32_e32 v39, 0xffff0000, v76
	v_pk_add_f32 v[4:5], v[4:5], v[38:39] neg_lo:[0,1] neg_hi:[0,1]
	s_waitcnt lgkmcnt(0)
	v_cvt_pk_bf16_f32 v96, v4, v5
	v_lshlrev_b32_e32 v4, 16, v77
	v_and_b32_e32 v5, 0xffff0000, v77
	v_pk_add_f32 v[4:5], v[6:7], v[4:5] neg_lo:[0,1] neg_hi:[0,1]
	s_barrier
	v_cvt_pk_bf16_f32 v97, v4, v5
	v_lshlrev_b32_e32 v4, 16, v78
	v_and_b32_e32 v5, 0xffff0000, v78
	v_pk_add_f32 v[4:5], v[8:9], v[4:5] neg_lo:[0,1] neg_hi:[0,1]
	s_nop 0
	v_cvt_pk_bf16_f32 v98, v4, v5
	v_lshlrev_b32_e32 v4, 16, v79
	v_and_b32_e32 v5, 0xffff0000, v79
	v_pk_add_f32 v[4:5], v[10:11], v[4:5] neg_lo:[0,1] neg_hi:[0,1]
	s_nop 0
	v_cvt_pk_bf16_f32 v99, v4, v5
	v_lshlrev_b32_e32 v4, 16, v108
	v_and_b32_e32 v5, 0xffff0000, v108
	v_pk_add_f32 v[4:5], v[12:13], v[4:5] neg_lo:[0,1] neg_hi:[0,1]
	s_nop 0
	v_cvt_pk_bf16_f32 v104, v4, v5
	v_lshlrev_b32_e32 v4, 16, v109
	v_and_b32_e32 v5, 0xffff0000, v109
	v_pk_add_f32 v[4:5], v[14:15], v[4:5] neg_lo:[0,1] neg_hi:[0,1]
	s_nop 0
	v_cvt_pk_bf16_f32 v105, v4, v5
	v_lshlrev_b32_e32 v4, 16, v110
	v_and_b32_e32 v5, 0xffff0000, v110
	v_pk_add_f32 v[4:5], v[16:17], v[4:5] neg_lo:[0,1] neg_hi:[0,1]
	s_nop 0
	v_cvt_pk_bf16_f32 v106, v4, v5
	v_lshlrev_b32_e32 v4, 16, v111
	v_and_b32_e32 v5, 0xffff0000, v111
	v_pk_add_f32 v[4:5], v[18:19], v[4:5] neg_lo:[0,1] neg_hi:[0,1]
	s_nop 0
	v_cvt_pk_bf16_f32 v107, v4, v5
	v_add_u32_e32 v4, s84, v0
	v_ashrrev_i32_e32 v5, 31, v4
	v_lshlrev_b64 v[4:5], 2, v[4:5]
	v_lshl_add_u64 v[140:141], s[10:11], 0, v[4:5]
	global_load_dword v2, v[140:141], off
	v_lshl_add_u64 v[136:137], s[14:15], 0, v[4:5]
	global_load_dword v190, v[136:137], off
	v_mul_u32_u24_e32 v4, 0x48, v183
	v_lshlrev_b32_e32 v4, 1, v4
	v_add3_u32 v174, 0, v20, v4
	ds_read_b128 v[4:7], v174
	ds_read_b128 v[20:23], v174 offset:9216
	ds_read_b128 v[8:11], v174 offset:18432
	s_waitcnt lgkmcnt(2)
	v_mfma_f32_16x16x32_bf16 v[12:15], v[4:7], v[76:79], 0
	s_waitcnt lgkmcnt(1)
	v_mfma_f32_16x16x32_bf16 v[12:15], v[20:23], v[76:79], v[12:15]
	v_mfma_f32_16x16x32_bf16 v[28:31], v[4:7], v[96:99], v[12:15]
	s_nop 6
	ds_read_b128 v[12:15], v174 offset:64
	ds_read_b128 v[24:27], v174 offset:9280
	ds_read_b128 v[16:19], v174 offset:18496
	s_waitcnt lgkmcnt(2)
	v_mfma_f32_16x16x32_bf16 v[28:31], v[12:15], v[108:111], v[28:31]
	s_waitcnt lgkmcnt(1)
	v_mfma_f32_16x16x32_bf16 v[28:31], v[24:27], v[108:111], v[28:31]
	v_mfma_f32_16x16x32_bf16 v[36:39], v[8:11], v[88:91], 0
	v_mfma_f32_16x16x32_bf16 v[32:35], v[12:15], v[104:107], v[28:31]
	s_waitcnt lgkmcnt(0)
	v_mfma_f32_16x16x32_bf16 v[28:31], v[16:19], v[100:103], v[36:39]
	s_waitcnt vmcnt(1)
	s_nop 4
	v_add_f32_e32 v32, v2, v32
	v_cmp_ngt_f32_e32 vcc, s74, v32
	v_xor_b32_e32 v191, 0x80000000, v32
	s_and_saveexec_b64 s[2:3], vcc
	s_xor_b64 s[4:5], exec, s[2:3]
	s_cbranch_execz .LBB0_228
	v_mul_f32_e32 v32, 0xbfb8aa3b, v32
	v_exp_f32_e32 v32, v32
	s_nop 0
	v_add_f32_e32 v32, 1.0, v32
	v_cmp_gt_f32_e32 vcc, s75, v32
	s_nop 1
	v_cndmask_b32_e64 v36, 0, 32, vcc
	v_ldexp_f32 v32, v32, v36
	v_log_f32_e32 v32, v32
	s_nop 0
	v_mul_f32_e32 v36, 0x3f317217, v32
	v_fma_f32 v36, v32, s88, -v36
	v_fmac_f32_e32 v36, 0x3377d1cf, v32
	v_fmac_f32_e32 v36, 0x3f317217, v32
	v_cmp_lt_f32_e64 s[2:3], |v32|, s70
	s_nop 1
	v_cndmask_b32_e64 v32, v32, v36, s[2:3]
	v_cndmask_b32_e32 v36, 0, v233, vcc
	v_sub_f32_e32 v191, v32, v36
